# attention tile loop hand-rescheduled: QK(T0),QK(T1),PV software-pipelined with 2nd S accumulator, exp/cvt in MFMA shadow, persistent LDS addresses
# speedup vs baseline: 1.0099x; 1.0051x over previous
; #define ATT_WAIT_V(n) asm volatile("s_waitcnt vmcnt(" #n ")" ::: "memory")
; __device__ __forceinline__ void attn_block(LAS unsigned char* lds, const Ptrs& P, int b, int h, int qb, float negMb, float lam, int tid, int wid, int lane) {
;     const int comp = wid & 1, quarter = wid >> 1, l31 = lane & 31, hh = lane >> 5;
;     const int NT = 2 * qb + 2;
;     const size_t tok0 = (size_t)b * SEQ;
;     const int qpos = qb * 128 + quarter * 32 + l31;
;     bf16x8 qf[8];
;     { const bf16* qp = P.Q + (tok0 + qpos) * 1024 + h * 256 + comp * 128 + hh * 8;
; #pragma unroll
;       for (int ks = 0; ks < 8; ++ks) qf[ks] = *(const bf16x8*)(qp + ks * 16); }
;     const unsigned ldsw = (unsigned)wid * 4096u;
;     const unsigned lds0 = (unsigned)__builtin_amdgcn_readfirstlane((int)(unsigned)(uintptr_t)lds);
;     unsigned kb0, kx16, vb0, vy16;
;     { int ln_ = lane; asm volatile("" : "+v"(ln_));
;       kb0 = (unsigned)(((16 * (wid & 3) + (ln_ >> 4)) * 1024 + h * 256 + (wid >> 2) * 128) * 2); kx16 = (unsigned)(((ln_ & 15) ^ (ln_ >> 4)) << 4);
;       vb0 = (unsigned)(((h * 256 + 32 * wid + (ln_ >> 3)) * M_TOK) * 2); vy16 = (unsigned)(((ln_ & 7) ^ (ln_ >> 4)) << 4);
;       asm volatile("" : "+v"(kb0), "+v"(kx16), "+v"(vb0), "+v"(vy16)); }
;     ...
;     f32x16 o[8];
; #pragma unroll
;     for (int e = 0; e < 8; ++e)
; #pragma unroll
;         for (int r = 0; r < 16; ++r) o[e][r] = 0.f;
;     float lsum = 0.f;
;     ATT_WAIT_V(0);
; #pragma unroll
;     for (int ks = 0; ks < 8; ++ks) asm volatile("" : "+v"(qf[ks]));
;     ATT_DMA(0, 0);
.LBB0_413:
	s_xor_b64 s[40:41], s[0:1], -1
	s_and_b64 s[0:1], s[0:1], exec
	s_cselect_b32 s2, s78, s77
	s_lshl_b32 s80, s2, 7
	s_add_i32 s80, s80, s50
	v_or_b32_e32 v194, s80, v203
	v_lshl_add_u64 v[18:19], s[20:21], 0, v[194:195]
	v_lshlrev_b64 v[18:19], 11, v[18:19]
	v_lshl_add_u64 v[18:19], v[198:199], 0, v[18:19]
	flat_load_dwordx4 v[190:193], v[18:19]
	flat_load_dwordx4 v[186:189], v[18:19] offset:32
	flat_load_dwordx4 v[182:185], v[18:19] offset:64
	flat_load_dwordx4 v[178:181], v[18:19] offset:96
	flat_load_dwordx4 v[174:177], v[18:19] offset:128
	flat_load_dwordx4 v[166:169], v[18:19] offset:160
	flat_load_dwordx4 v[170:173], v[18:19] offset:192
	flat_load_dwordx4 v[162:165], v[18:19] offset:224
	v_mov_b32_e32 v51, v1
	s_lshl_b32 s82, s2, 17
	v_ashrrev_i32_e32 v52, 4, v51
	v_lshrrev_b32_e32 v53, 3, v51
	v_add_u32_e32 v54, s51, v52
	v_bitop3_b32 v55, v51, v52, 15 bitop3:0x6c
	v_bitop3_b32 v51, v51, v52, 7 bitop3:0x6c
	v_add_lshl_u32 v53, s79, v53, 16
	v_lshl_add_u32 v52, v54, 11, s4
	v_lshlrev_b32_e32 v54, 4, v55
	v_lshlrev_b32_e32 v51, 4, v51
	s_waitcnt vmcnt(0)
	v_mov_b32_e32 v194, 0
	v_add_u32_e32 v206, v52, v54
	v_xor_b32_e32 v55, 64, v54
	v_xor_b32_e32 v56, 0x80, v54
	v_add3_u32 v208, v52, v55, s71
	v_xor_b32_e32 v54, 0xc0, v54
	v_add3_u32 v209, v52, v56, s72
	v_add3_u32 v210, v52, v54, s73
	v_add_u32_e32 v207, v53, v51
	v_xad_u32 v51, v51, 64, v53
	v_add_u32_e32 v211, 0x80000, v51
	v_add_u32_e32 v212, 0x100000, v207
	v_add_u32_e32 v213, 0x180000, v51
	s_mov_b32 s81, 0
	s_mov_b64 s[0:1], s[38:39]
	s_mov_b64 s[42:43], s[36:37]
	v_mov_b32_e32 v18, 0
	v_mov_b32_e32 v34, 0
	v_mov_b32_e32 v50, 0
	v_mov_b32_e32 v19, v194
	v_mov_b32_e32 v20, v194
	v_mov_b32_e32 v21, v194
	v_mov_b32_e32 v22, v194
	v_mov_b32_e32 v23, v194
	v_mov_b32_e32 v24, v194
	v_mov_b32_e32 v25, v194
	v_mov_b32_e32 v26, v194
	v_mov_b32_e32 v27, v194
	v_mov_b32_e32 v28, v194
	v_mov_b32_e32 v29, v194
	v_mov_b32_e32 v30, v194
	v_mov_b32_e32 v31, v194
	v_mov_b32_e32 v32, v194
	v_mov_b32_e32 v33, v194
	v_mov_b32_e32 v35, v194
	v_mov_b32_e32 v36, v194
	v_mov_b32_e32 v37, v194
	v_mov_b32_e32 v38, v194
	v_mov_b32_e32 v39, v194
	v_mov_b32_e32 v40, v194
	v_mov_b32_e32 v41, v194
	v_mov_b32_e32 v42, v194
	v_mov_b32_e32 v43, v194
	v_mov_b32_e32 v44, v194
	v_mov_b32_e32 v45, v194
	v_mov_b32_e32 v46, v194
	v_mov_b32_e32 v47, v194
	v_mov_b32_e32 v48, v194
	v_mov_b32_e32 v49, v194
	s_bitset1_b32 s82, 16
	v_mov_b32_e32 v51, v194
	v_mov_b32_e32 v52, v194
	v_mov_b32_e32 v53, v194
	v_mov_b32_e32 v54, v194
	v_mov_b32_e32 v55, v194
	v_mov_b32_e32 v56, v194
	v_mov_b32_e32 v57, v194
	v_mov_b32_e32 v58, v194
	s_waitcnt vmcnt(0) lgkmcnt(0)
	s_mov_b32 s2, m0
	s_mov_b32 m0, s54
	s_nop 0
	global_load_lds_dwordx4 v206, s[24:25]
	s_mov_b32 m0, s2
	v_mov_b32_e32 v59, v194
	s_mov_b32 s2, m0
	s_mov_b32 m0, s55
	s_nop 0
	global_load_lds_dwordx4 v208, s[24:25]
	s_mov_b32 m0, s2
	v_mov_b32_e32 v60, v194
	s_mov_b32 s2, m0
	s_mov_b32 m0, s56
	s_nop 0
	global_load_lds_dwordx4 v209, s[24:25]
	s_mov_b32 m0, s2
	v_mov_b32_e32 v61, v194
	s_mov_b32 s2, m0
	s_mov_b32 m0, s57
	s_nop 0
	global_load_lds_dwordx4 v210, s[24:25]
	s_mov_b32 m0, s2
	v_mov_b32_e32 v62, v194
	s_mov_b32 s2, m0
	s_mov_b32 m0, s61
	s_nop 0
	global_load_lds_dwordx4 v207, s[26:27]
	s_mov_b32 m0, s2
	v_mov_b32_e32 v63, v194
	s_mov_b32 s2, m0
	s_mov_b32 m0, s62
	s_nop 0
	global_load_lds_dwordx4 v211, s[26:27]
	s_mov_b32 m0, s2
	v_mov_b32_e32 v64, v194
	s_mov_b32 s2, m0
	s_mov_b32 m0, s63
	s_nop 0
	global_load_lds_dwordx4 v212, s[26:27]
	s_mov_b32 m0, s2
	v_mov_b32_e32 v65, v194
	s_mov_b32 s2, m0
	s_mov_b32 m0, s64
	s_nop 0
	global_load_lds_dwordx4 v213, s[26:27]
	s_mov_b32 m0, s2
	v_mov_b32_e32 v66, 0
	v_mov_b32_e32 v67, v194
	v_mov_b32_e32 v68, v194
	v_mov_b32_e32 v69, v194
	v_mov_b32_e32 v70, v194
	v_mov_b32_e32 v71, v194
	v_mov_b32_e32 v72, v194
	v_mov_b32_e32 v73, v194
	v_mov_b32_e32 v74, v194
	v_mov_b32_e32 v75, v194
	v_mov_b32_e32 v76, v194
	v_mov_b32_e32 v77, v194
	v_mov_b32_e32 v78, v194
	v_mov_b32_e32 v79, v194
	v_mov_b32_e32 v80, v194
	v_mov_b32_e32 v81, v194
	v_mov_b32_e32 v82, 0
	v_mov_b32_e32 v83, v194
	v_mov_b32_e32 v84, v194
	v_mov_b32_e32 v85, v194
	v_mov_b32_e32 v86, v194
	v_mov_b32_e32 v87, v194
	v_mov_b32_e32 v88, v194
	v_mov_b32_e32 v89, v194
	v_mov_b32_e32 v90, v194
	v_mov_b32_e32 v91, v194
	v_mov_b32_e32 v92, v194
	v_mov_b32_e32 v93, v194
	v_mov_b32_e32 v94, v194
	v_mov_b32_e32 v95, v194
	v_mov_b32_e32 v96, v194
	v_mov_b32_e32 v97, v194
	v_mov_b32_e32 v98, 0
	v_mov_b32_e32 v99, v194
	v_mov_b32_e32 v100, v194
	v_mov_b32_e32 v101, v194
	v_mov_b32_e32 v102, v194
	v_mov_b32_e32 v103, v194
	v_mov_b32_e32 v104, v194
	v_mov_b32_e32 v105, v194
	v_mov_b32_e32 v106, v194
	v_mov_b32_e32 v107, v194
	v_mov_b32_e32 v108, v194
	v_mov_b32_e32 v109, v194
	v_mov_b32_e32 v110, v194
	v_mov_b32_e32 v111, v194
	v_mov_b32_e32 v112, v194
	v_mov_b32_e32 v113, v194
	v_mov_b32_e32 v114, 0
	v_mov_b32_e32 v115, v194
	v_mov_b32_e32 v116, v194
	v_mov_b32_e32 v117, v194
	v_mov_b32_e32 v118, v194
	v_mov_b32_e32 v119, v194
	v_mov_b32_e32 v120, v194
	v_mov_b32_e32 v121, v194
	v_mov_b32_e32 v122, v194
	v_mov_b32_e32 v123, v194
	v_mov_b32_e32 v124, v194
	v_mov_b32_e32 v125, v194
	v_mov_b32_e32 v126, v194
	v_mov_b32_e32 v127, v194
	v_mov_b32_e32 v128, v194
	v_mov_b32_e32 v129, v194
	v_mov_b32_e32 v130, 0
	v_mov_b32_e32 v131, v194
	v_mov_b32_e32 v132, v194
	v_mov_b32_e32 v133, v194
	v_mov_b32_e32 v134, v194
	v_mov_b32_e32 v135, v194
	v_mov_b32_e32 v136, v194
	v_mov_b32_e32 v137, v194
	v_mov_b32_e32 v138, v194
	v_mov_b32_e32 v139, v194
	v_mov_b32_e32 v140, v194
	v_mov_b32_e32 v141, v194
	v_mov_b32_e32 v142, v194
	v_mov_b32_e32 v143, v194
	v_mov_b32_e32 v144, v194
; #define LAS __attribute__((address_space(3)))
; #define LDS_WAIT() asm volatile("s_waitcnt lgkmcnt(0)" ::: "memory")
; __device__ __forceinline__ int pi32(int i) { return (i & ~12) | ((i & 4) << 1) | ((i & 8) >> 1); }
; #define ATT_WAIT_V(n) asm volatile("s_waitcnt vmcnt(" #n ")" ::: "memory")
; #define ATT_BAR() do { asm volatile("" ::: "memory"); __builtin_amdgcn_s_barrier(); asm volatile("" ::: "memory"); } while (0)
; __device__ __forceinline__ void attn_block(LAS unsigned char* lds, const Ptrs& P, int b, int h, int qb, float negMb, float lam, int tid, int wid, int lane) {
;     ...
;     for (int t = 0; t < NT; ++t) {
;         ATT_WAIT_V(0);
;         LDS_WAIT();
;         ATT_BAR();
;         const bool more = t + 1 < NT;
;         if (more && early) ATT_DMA(t + 1, (t + 1) & 1);
;         const bool active = (quarter >= 2) || more;
;         const LAS unsigned char* base = lds + (t & 1) * BUF;
;         int ln2 = lane; asm volatile("" : "+v"(ln2));
;         const int l31b = ln2 & 31, hhb = ln2 >> 5;
;         const int krow = pi32(l31b), kx = krow & 15;
;         const int koffr = comp * 16384 + krow * 256;
;         const int vx = (l31b >> 1) & 7;
;         const int voffr = V_OFF + l31b * 128;
; #pragma unroll
;         for (int T = 0; T < 2; ++T) {
;             if (T == 1 && more && !early) ATT_DMA(t + 1, (t + 1) & 1);
;             if (active) {
;                 f32x16 s;
; #pragma unroll
;                 for (int r = 0; r < 16; ++r) s[r] = negMb;
; #pragma unroll
;                 for (int ks = 0; ks < 8; ++ks) {
;                     const bf16x8 kf = *(const LAS bf16x8*)(base + koffr + T * 8192 + (((2 * ks + hhb) ^ kx) << 4));
;                     s = __builtin_amdgcn_mfma_f32_32x32x16_bf16(kf, qf[ks], s, 0, 0, 0);
;                 }
;                 float ps = 0.f;
; #pragma unroll
;                 for (int r = 0; r < 16; ++r) { s[r] = __builtin_amdgcn_exp2f(s[r]); ps += s[r]; }
	v_mov_b32_e32 v145, v194
	v_lshrrev_b32_e32 v226, 5, v1
	v_and_b32_e32 v227, 19, v1
	v_lshlrev_b32_e32 v228, 1, v1
	v_and_b32_e32 v228, 8, v228
	v_lshrrev_b32_e32 v229, 1, v1
	v_and_b32_e32 v230, 4, v229
	v_or3_b32 v227, v227, v228, v230
	v_and_b32_e32 v231, 15, v227
	v_lshl_add_u32 v232, v227, 8, s65
	v_xor_b32_e32 v233, v226, v231
	v_lshl_add_u32 v214, v233, 4, v232
	v_add_u32_e32 v233, 2, v226
	v_xor_b32_e32 v233, v233, v231
	v_lshl_add_u32 v215, v233, 4, v232
	v_add_u32_e32 v233, 4, v226
	v_xor_b32_e32 v233, v233, v231
	v_lshl_add_u32 v216, v233, 4, v232
	v_add_u32_e32 v233, 6, v226
	v_xor_b32_e32 v233, v233, v231
	v_lshl_add_u32 v217, v233, 4, v232
	v_add_u32_e32 v233, 8, v226
	v_xor_b32_e32 v233, v233, v231
	v_lshl_add_u32 v218, v233, 4, v232
	v_add_u32_e32 v233, 10, v226
	v_xor_b32_e32 v233, v233, v231
	v_lshl_add_u32 v219, v233, 4, v232
	v_add_u32_e32 v233, 12, v226
	v_xor_b32_e32 v233, v233, v231
	v_lshl_add_u32 v220, v233, 4, v232
	v_add_u32_e32 v233, 14, v226
	v_xor_b32_e32 v233, v233, v231
	v_lshl_add_u32 v221, v233, 4, v232
	v_and_b32_e32 v234, 7, v229
	v_and_b32_e32 v235, 31, v1
	v_lshlrev_b32_e32 v235, 7, v235
	v_xor_b32_e32 v233, v226, v234
	v_lshl_add_u32 v222, v233, 4, v235
	v_add_u32_e32 v233, 2, v226
	v_xor_b32_e32 v233, v233, v234
	v_lshl_add_u32 v223, v233, 4, v235
	v_add_u32_e32 v233, 4, v226
	v_xor_b32_e32 v233, v233, v234
	v_lshl_add_u32 v224, v233, 4, v235
	v_add_u32_e32 v233, 6, v226
	v_xor_b32_e32 v233, v233, v234
	v_lshl_add_u32 v225, v233, 4, v235
	v_mov_b32_e32 v254, 0
	v_mov_b32_e32 v255, 0
	s_branch .Lat_tile
.Lat_tile:
	s_waitcnt vmcnt(0)
	s_waitcnt lgkmcnt(0)
	s_barrier
	s_add_i32 s44, s81, 0x10000
	s_and_b32 s83, s44, 0x10000
	s_add_i32 s84, s83, s54
	s_add_i32 s85, s83, s61
	s_and_b64 vcc, exec, s[12:13]
	s_cbranch_vccnz .Lat_qk
	s_mov_b32 s44, m0
	s_mov_b32 m0, s84
	s_nop 0
	global_load_lds_dwordx4 v206, s[0:1]
	s_mov_b32 m0, s44
	s_add_i32 s44, s84, 0x400
	s_mov_b32 s45, m0
	s_mov_b32 m0, s44
	s_nop 0
	global_load_lds_dwordx4 v208, s[0:1]
	s_mov_b32 m0, s45
	s_add_i32 s44, s84, 0x800
	s_mov_b32 s45, m0
	s_mov_b32 m0, s44
	s_nop 0
	global_load_lds_dwordx4 v209, s[0:1]
	s_mov_b32 m0, s45
	s_add_i32 s44, s84, 0xc00
	s_mov_b32 s45, m0
	s_mov_b32 m0, s44
	s_nop 0
	global_load_lds_dwordx4 v210, s[0:1]
	s_mov_b32 m0, s45
	s_mov_b32 s44, m0
	s_mov_b32 m0, s85
	s_nop 0
	global_load_lds_dwordx4 v207, s[42:43]
	s_mov_b32 m0, s44
	s_add_i32 s44, s85, 0x400
	s_mov_b32 s45, m0
	s_mov_b32 m0, s44
	s_nop 0
	global_load_lds_dwordx4 v211, s[42:43]
	s_mov_b32 m0, s45
	s_add_i32 s44, s85, 0x800
	s_mov_b32 s45, m0
	s_mov_b32 m0, s44
	s_nop 0
	global_load_lds_dwordx4 v212, s[42:43]
	s_mov_b32 m0, s45
	s_add_i32 s44, s85, 0xc00
	s_mov_b32 s45, m0
	s_mov_b32 m0, s44
	s_nop 0
	global_load_lds_dwordx4 v213, s[42:43]
	s_mov_b32 m0, s45
.Lat_qk:
	ds_read_b128 v[226:229], v214
	ds_read_b128 v[230:233], v215
	ds_read_b128 v[234:237], v216
	s_waitcnt lgkmcnt(2)
	v_mfma_f32_32x32x16_bf16 v[146:161], v[226:229], v[190:193], v[2:17]
	ds_read_b128 v[226:229], v217
	s_waitcnt lgkmcnt(2)
	v_mfma_f32_32x32x16_bf16 v[146:161], v[230:233], v[186:189], v[146:161]
	ds_read_b128 v[230:233], v218
	s_waitcnt lgkmcnt(2)
	v_mfma_f32_32x32x16_bf16 v[146:161], v[234:237], v[182:185], v[146:161]
	ds_read_b128 v[234:237], v219
	s_waitcnt lgkmcnt(2)
	v_mfma_f32_32x32x16_bf16 v[146:161], v[226:229], v[178:181], v[146:161]
	ds_read_b128 v[226:229], v220
	s_waitcnt lgkmcnt(2)
	v_mfma_f32_32x32x16_bf16 v[146:161], v[230:233], v[174:177], v[146:161]
	ds_read_b128 v[230:233], v221
	s_waitcnt lgkmcnt(2)
	v_mfma_f32_32x32x16_bf16 v[146:161], v[234:237], v[166:169], v[146:161]
	ds_read_b128 v[234:237], v214 offset:8192
	s_waitcnt lgkmcnt(2)
	v_mfma_f32_32x32x16_bf16 v[146:161], v[226:229], v[170:173], v[146:161]
	ds_read_b128 v[226:229], v215 offset:8192
	s_waitcnt lgkmcnt(2)
	v_mfma_f32_32x32x16_bf16 v[146:161], v[230:233], v[162:165], v[146:161]
	ds_read_b128 v[230:233], v216 offset:8192
	s_waitcnt lgkmcnt(2)
	v_mfma_f32_32x32x16_bf16 v[238:253], v[234:237], v[190:193], v[2:17]
	ds_read_b128 v[234:237], v217 offset:8192
	s_waitcnt lgkmcnt(2)
	v_mfma_f32_32x32x16_bf16 v[238:253], v[226:229], v[186:189], v[238:253]
	ds_read_b128 v[226:229], v218 offset:8192
	s_waitcnt lgkmcnt(2)
	v_mfma_f32_32x32x16_bf16 v[238:253], v[230:233], v[182:185], v[238:253]
	ds_read_b128 v[230:233], v219 offset:8192
	s_waitcnt lgkmcnt(2)
	v_mfma_f32_32x32x16_bf16 v[238:253], v[234:237], v[178:181], v[238:253]
	ds_read_b128 v[234:237], v220 offset:8192
	v_exp_f32_e32 v146, v146
	v_exp_f32_e32 v147, v147
	v_exp_f32_e32 v148, v148
	s_waitcnt lgkmcnt(2)
	v_mfma_f32_32x32x16_bf16 v[238:253], v[226:229], v[174:177], v[238:253]
	v_exp_f32_e32 v149, v149
	v_exp_f32_e32 v150, v150
	v_exp_f32_e32 v151, v151
	ds_read_b128 v[226:229], v221 offset:8192
	s_waitcnt lgkmcnt(2)
	v_mfma_f32_32x32x16_bf16 v[238:253], v[230:233], v[166:169], v[238:253]
	v_exp_f32_e32 v152, v152
	v_exp_f32_e32 v153, v153
	v_add_f32_e32 v254, v254, v146
	v_add_f32_e32 v255, v255, v147
	ds_read_b128 v[230:233], v222 offset:32768
	s_waitcnt lgkmcnt(2)
	v_mfma_f32_32x32x16_bf16 v[238:253], v[234:237], v[170:173], v[238:253]
	v_add_f32_e32 v254, v254, v148
	v_add_f32_e32 v255, v255, v149
	v_add_f32_e32 v254, v254, v150
	v_add_f32_e32 v255, v255, v151
	v_add_f32_e32 v254, v254, v152
	ds_read_b128 v[234:237], v222 offset:36864
	s_waitcnt lgkmcnt(2)
	v_mfma_f32_32x32x16_bf16 v[238:253], v[226:229], v[162:165], v[238:253]
	v_add_f32_e32 v255, v255, v153
	v_cvt_pk_bf16_f32 v146, v146, v147
	v_cvt_pk_bf16_f32 v147, v148, v149
	v_cvt_pk_bf16_f32 v148, v150, v151
	v_cvt_pk_bf16_f32 v149, v152, v153
	ds_read_b128 v[226:229], v222 offset:40960
	s_waitcnt lgkmcnt(2)
; #define LAS __attribute__((address_space(3)))
; __device__ __forceinline__ unsigned pk2(float lo, float hi) { return pg8::cvt_pk_bf16(lo, hi); }
; __device__ __forceinline__ void attn_block(LAS unsigned char* lds, const Ptrs& P, int b, int h, int qb, float negMb, float lam, int tid, int wid, int lane) {
;     ...
;                 float ps = 0.f;
; #pragma unroll
;                 for (int r = 0; r < 16; ++r) { s[r] = __builtin_amdgcn_exp2f(s[r]); ps += s[r]; }
;                 lsum += ps;
; #pragma unroll
;                 for (int sI = 0; sI < 2; ++sI) { v4u w;
; #pragma unroll
;                     for (int j = 0; j < 4; ++j) w[j] = pk2(s[8 * sI + 2 * j], s[8 * sI + 2 * j + 1]);
;                     const bf16x8 pf = __builtin_bit_cast(bf16x8, w);
;                     const LAS unsigned char* vb = base + voffr + (((2 * (2 * T + sI) + hhb) ^ vx) << 4);
; #pragma unroll
;                     for (int e = 0; e < 8; ++e) {
;                         const bf16x8 vf = *(const LAS bf16x8*)(vb + e * 4096);
;                         o[e] = __builtin_amdgcn_mfma_f32_32x32x16_bf16(vf, pf, o[e], 0, 0, 0);
;                     }
;                 }
	v_mfma_f32_32x32x16_bf16 v[130:145], v[230:233], v[146:149], v[130:145]
	v_exp_f32_e32 v154, v154
	v_exp_f32_e32 v155, v155
	v_exp_f32_e32 v156, v156
	ds_read_b128 v[230:233], v222 offset:45056
	s_waitcnt lgkmcnt(2)
	v_mfma_f32_32x32x16_bf16 v[114:129], v[234:237], v[146:149], v[114:129]
	v_exp_f32_e32 v157, v157
	v_exp_f32_e32 v158, v158
	v_exp_f32_e32 v159, v159
	ds_read_b128 v[234:237], v222 offset:49152
	s_waitcnt lgkmcnt(2)
	v_mfma_f32_32x32x16_bf16 v[98:113], v[226:229], v[146:149], v[98:113]
	v_exp_f32_e32 v160, v160
	v_exp_f32_e32 v161, v161
	v_add_f32_e32 v254, v254, v154
	ds_read_b128 v[226:229], v222 offset:53248
	s_waitcnt lgkmcnt(2)
	v_mfma_f32_32x32x16_bf16 v[82:97], v[230:233], v[146:149], v[82:97]
	v_add_f32_e32 v255, v255, v155
	v_add_f32_e32 v254, v254, v156
	v_add_f32_e32 v255, v255, v157
	ds_read_b128 v[230:233], v222 offset:57344
	s_waitcnt lgkmcnt(2)
	v_mfma_f32_32x32x16_bf16 v[66:81], v[234:237], v[146:149], v[66:81]
	v_add_f32_e32 v254, v254, v158
	v_add_f32_e32 v255, v255, v159
	v_add_f32_e32 v254, v254, v160
	ds_read_b128 v[234:237], v222 offset:61440
	s_waitcnt lgkmcnt(2)
	v_mfma_f32_32x32x16_bf16 v[50:65], v[226:229], v[146:149], v[50:65]
	v_add_f32_e32 v255, v255, v161
	v_cvt_pk_bf16_f32 v154, v154, v155
	v_cvt_pk_bf16_f32 v155, v156, v157
	ds_read_b128 v[226:229], v223 offset:32768
	s_waitcnt lgkmcnt(2)
	v_mfma_f32_32x32x16_bf16 v[34:49], v[230:233], v[146:149], v[34:49]
	v_cvt_pk_bf16_f32 v156, v158, v159
	v_cvt_pk_bf16_f32 v157, v160, v161
	ds_read_b128 v[230:233], v223 offset:36864
	s_waitcnt lgkmcnt(2)
	v_mfma_f32_32x32x16_bf16 v[18:33], v[234:237], v[146:149], v[18:33]
	ds_read_b128 v[234:237], v223 offset:40960
	s_waitcnt lgkmcnt(2)
	v_mfma_f32_32x32x16_bf16 v[130:145], v[226:229], v[154:157], v[130:145]
	v_exp_f32_e32 v238, v238
	v_exp_f32_e32 v239, v239
	v_exp_f32_e32 v240, v240
	ds_read_b128 v[226:229], v223 offset:45056
	s_waitcnt lgkmcnt(2)
	v_mfma_f32_32x32x16_bf16 v[114:129], v[230:233], v[154:157], v[114:129]
	v_exp_f32_e32 v241, v241
	v_exp_f32_e32 v242, v242
	v_exp_f32_e32 v243, v243
	ds_read_b128 v[230:233], v223 offset:49152
	s_waitcnt lgkmcnt(2)
	v_mfma_f32_32x32x16_bf16 v[98:113], v[234:237], v[154:157], v[98:113]
	v_exp_f32_e32 v244, v244
	v_exp_f32_e32 v245, v245
	v_add_f32_e32 v254, v254, v238
	ds_read_b128 v[234:237], v223 offset:53248
	s_waitcnt lgkmcnt(2)
	v_mfma_f32_32x32x16_bf16 v[82:97], v[226:229], v[154:157], v[82:97]
	v_add_f32_e32 v255, v255, v239
	v_add_f32_e32 v254, v254, v240
	v_add_f32_e32 v255, v255, v241
	ds_read_b128 v[226:229], v223 offset:57344
	s_waitcnt lgkmcnt(2)
	v_mfma_f32_32x32x16_bf16 v[66:81], v[230:233], v[154:157], v[66:81]
	v_add_f32_e32 v254, v254, v242
	v_add_f32_e32 v255, v255, v243
	v_add_f32_e32 v254, v254, v244
	ds_read_b128 v[230:233], v223 offset:61440
	s_waitcnt lgkmcnt(2)
	v_mfma_f32_32x32x16_bf16 v[50:65], v[234:237], v[154:157], v[50:65]
	v_add_f32_e32 v255, v255, v245
	v_cvt_pk_bf16_f32 v238, v238, v239
	v_cvt_pk_bf16_f32 v239, v240, v241
	ds_read_b128 v[234:237], v224 offset:32768
	s_waitcnt lgkmcnt(2)
	v_mfma_f32_32x32x16_bf16 v[34:49], v[226:229], v[154:157], v[34:49]
	v_cvt_pk_bf16_f32 v240, v242, v243
	v_cvt_pk_bf16_f32 v241, v244, v245
	ds_read_b128 v[226:229], v224 offset:36864
	s_waitcnt lgkmcnt(2)
	v_mfma_f32_32x32x16_bf16 v[18:33], v[230:233], v[154:157], v[18:33]
	ds_read_b128 v[230:233], v224 offset:40960
	s_andn2_b64 vcc, exec, s[12:13]
	s_cbranch_vccnz .Lat_pv1
	s_mov_b32 s44, m0
	s_mov_b32 m0, s84
	s_nop 0
	global_load_lds_dwordx4 v206, s[0:1]
	s_mov_b32 m0, s44
	s_add_i32 s44, s84, 0x400
	s_mov_b32 s45, m0
	s_mov_b32 m0, s44
	s_nop 0
	global_load_lds_dwordx4 v208, s[0:1]
	s_mov_b32 m0, s45
	s_add_i32 s44, s84, 0x800
	s_mov_b32 s45, m0
	s_mov_b32 m0, s44
	s_nop 0
	global_load_lds_dwordx4 v209, s[0:1]
	s_mov_b32 m0, s45
	s_add_i32 s44, s84, 0xc00
	s_mov_b32 s45, m0
	s_mov_b32 m0, s44
	s_nop 0
	global_load_lds_dwordx4 v210, s[0:1]
	s_mov_b32 m0, s45
	s_mov_b32 s44, m0
	s_mov_b32 m0, s85
	s_nop 0
	global_load_lds_dwordx4 v207, s[42:43]
	s_mov_b32 m0, s44
	s_add_i32 s44, s85, 0x400
	s_mov_b32 s45, m0
	s_mov_b32 m0, s44
	s_nop 0
	global_load_lds_dwordx4 v211, s[42:43]
	s_mov_b32 m0, s45
	s_add_i32 s44, s85, 0x800
	s_mov_b32 s45, m0
	s_mov_b32 m0, s44
	s_nop 0
	global_load_lds_dwordx4 v212, s[42:43]
	s_mov_b32 m0, s45
	s_add_i32 s44, s85, 0xc00
	s_mov_b32 s45, m0
	s_mov_b32 m0, s44
	s_nop 0
	global_load_lds_dwordx4 v213, s[42:43]
	s_mov_b32 m0, s45
; #define LAS __attribute__((address_space(3)))
; __device__ __forceinline__ unsigned pk2(float lo, float hi) { return pg8::cvt_pk_bf16(lo, hi); }
; __device__ __forceinline__ void attn_block(LAS unsigned char* lds, const Ptrs& P, int b, int h, int qb, float negMb, float lam, int tid, int wid, int lane) {
;     ...
;                 for (int sI = 0; sI < 2; ++sI) { v4u w;
; #pragma unroll
;                     for (int j = 0; j < 4; ++j) w[j] = pk2(s[8 * sI + 2 * j], s[8 * sI + 2 * j + 1]);
;                     const bf16x8 pf = __builtin_bit_cast(bf16x8, w);
;                     const LAS unsigned char* vb = base + voffr + (((2 * (2 * T + sI) + hhb) ^ vx) << 4);
; #pragma unroll
;                     for (int e = 0; e < 8; ++e) {
;                         const bf16x8 vf = *(const LAS bf16x8*)(vb + e * 4096);
;                         o[e] = __builtin_amdgcn_mfma_f32_32x32x16_bf16(vf, pf, o[e], 0, 0, 0);
;                     }
;                 }
;             }
;         }
;     }
.Lat_pv1:
	s_waitcnt lgkmcnt(2)
	v_mfma_f32_32x32x16_bf16 v[130:145], v[234:237], v[238:241], v[130:145]
	v_exp_f32_e32 v246, v246
	v_exp_f32_e32 v247, v247
	v_exp_f32_e32 v248, v248
	ds_read_b128 v[234:237], v224 offset:45056
	s_waitcnt lgkmcnt(2)
	v_mfma_f32_32x32x16_bf16 v[114:129], v[226:229], v[238:241], v[114:129]
	v_exp_f32_e32 v249, v249
	v_exp_f32_e32 v250, v250
	v_exp_f32_e32 v251, v251
	ds_read_b128 v[226:229], v224 offset:49152
	s_waitcnt lgkmcnt(2)
	v_mfma_f32_32x32x16_bf16 v[98:113], v[230:233], v[238:241], v[98:113]
	v_exp_f32_e32 v252, v252
	v_exp_f32_e32 v253, v253
	v_add_f32_e32 v254, v254, v246
	ds_read_b128 v[230:233], v224 offset:53248
	s_waitcnt lgkmcnt(2)
	v_mfma_f32_32x32x16_bf16 v[82:97], v[234:237], v[238:241], v[82:97]
	v_add_f32_e32 v255, v255, v247
	v_add_f32_e32 v254, v254, v248
	v_add_f32_e32 v255, v255, v249
	ds_read_b128 v[234:237], v224 offset:57344
	s_waitcnt lgkmcnt(2)
	v_mfma_f32_32x32x16_bf16 v[66:81], v[226:229], v[238:241], v[66:81]
	v_add_f32_e32 v254, v254, v250
	v_add_f32_e32 v255, v255, v251
	v_add_f32_e32 v254, v254, v252
	ds_read_b128 v[226:229], v224 offset:61440
	s_waitcnt lgkmcnt(2)
	v_mfma_f32_32x32x16_bf16 v[50:65], v[230:233], v[238:241], v[50:65]
	v_add_f32_e32 v255, v255, v253
	v_cvt_pk_bf16_f32 v246, v246, v247
	v_cvt_pk_bf16_f32 v247, v248, v249
	ds_read_b128 v[230:233], v225 offset:32768
	s_waitcnt lgkmcnt(2)
	v_mfma_f32_32x32x16_bf16 v[34:49], v[234:237], v[238:241], v[34:49]
	v_cvt_pk_bf16_f32 v248, v250, v251
	v_cvt_pk_bf16_f32 v249, v252, v253
	ds_read_b128 v[234:237], v225 offset:36864
	s_waitcnt lgkmcnt(2)
	v_mfma_f32_32x32x16_bf16 v[18:33], v[226:229], v[238:241], v[18:33]
	ds_read_b128 v[226:229], v225 offset:40960
	s_waitcnt lgkmcnt(2)
	v_mfma_f32_32x32x16_bf16 v[130:145], v[230:233], v[246:249], v[130:145]
	v_xor_b32_e32 v214, 0x10000, v214
	v_xor_b32_e32 v215, 0x10000, v215
	ds_read_b128 v[230:233], v225 offset:45056
	s_waitcnt lgkmcnt(2)
	v_mfma_f32_32x32x16_bf16 v[114:129], v[234:237], v[246:249], v[114:129]
	v_xor_b32_e32 v216, 0x10000, v216
	v_xor_b32_e32 v217, 0x10000, v217
	ds_read_b128 v[234:237], v225 offset:49152
	s_waitcnt lgkmcnt(2)
	v_mfma_f32_32x32x16_bf16 v[98:113], v[226:229], v[246:249], v[98:113]
	v_xor_b32_e32 v218, 0x10000, v218
	v_xor_b32_e32 v219, 0x10000, v219
	ds_read_b128 v[226:229], v225 offset:53248
	s_waitcnt lgkmcnt(2)
	v_mfma_f32_32x32x16_bf16 v[82:97], v[230:233], v[246:249], v[82:97]
	v_xor_b32_e32 v220, 0x10000, v220
	v_xor_b32_e32 v221, 0x10000, v221
	ds_read_b128 v[230:233], v225 offset:57344
	s_waitcnt lgkmcnt(2)
	v_mfma_f32_32x32x16_bf16 v[66:81], v[234:237], v[246:249], v[66:81]
	v_xor_b32_e32 v222, 0x10000, v222
	v_xor_b32_e32 v223, 0x10000, v223
	ds_read_b128 v[234:237], v225 offset:61440
	s_waitcnt lgkmcnt(2)
	v_mfma_f32_32x32x16_bf16 v[50:65], v[226:229], v[246:249], v[50:65]
	v_xor_b32_e32 v224, 0x10000, v224
	s_waitcnt lgkmcnt(1)
	v_mfma_f32_32x32x16_bf16 v[34:49], v[230:233], v[246:249], v[34:49]
	v_xor_b32_e32 v225, 0x10000, v225
	s_waitcnt lgkmcnt(0)
	v_mfma_f32_32x32x16_bf16 v[18:33], v[234:237], v[246:249], v[18:33]
	s_add_i32 s81, s81, 0x10000
	s_add_u32 s42, s42, 0x80
	s_addc_u32 s43, s43, 0
	s_add_u32 s0, s0, 0x20000
	s_addc_u32 s1, s1, 0
	s_cmp_eq_u32 s82, s81
	s_cbranch_scc0 .Lat_tile
	s_not_b64 s[2:3], s[12:13]
	s_nop 0
	v_add_f32_e32 v194, v194, v254
	v_add_f32_e32 v194, v194, v255
